# EpiRes (Wo/Down) epilogue fast paths: streamed base loads via tuple pool, counted vmcnt, no store waits
# speedup vs baseline: 1.0388x; 1.0134x over previous
; __device__ __forceinline__ unsigned pkbf(float lo, float hi) { f32x2_t v = {lo, hi}; bf16x2_t b = __builtin_convertvector(v, bf16x2_t); return __builtin_bit_cast(unsigned, b); }
;     __device__ __forceinline__ void operator()(const f32x4 (&acc)[2][2][4][2], const pg8::Unit& u, int wr, int wc, int fr, int fq) const {
;     ...
;         const bool bf = isctx || base_f32, of = isctx || out_f32;
;         const float* bpf = isctx ? base_ctx : (const float*)base_lat; float* opf = isctx ? out_ctx : (float*)out_lat;
;         const bf16_t* bph = (const bf16_t*)base_lat; bf16_t* oph = (bf16_t*)out_lat;
; #pragma unroll
;         for (int ai = 0; ai < 2; ++ai)
; #pragma unroll
;             for (int m = 0; m < 4; ++m) { const size_t off = (size_t)(row0 + ai * 128 + m * 16) * DM + col0;
; #pragma unroll
;                 for (int bj = 0; bj < 2; ++bj) {
;                     f32x4 b0, b1;
;                     if (bf) { b0 = *(const f32x4*)(bpf + off + bj * 128); b1 = *(const f32x4*)(bpf + off + bj * 128 + 4); }
;                     else { const u32x4 w = *(const u32x4*)(bph + off + bj * 128);
;                         b0 = (f32x4){__uint_as_float(w.x << 16), __uint_as_float(w.x & 0xffff0000u), __uint_as_float(w.y << 16), __uint_as_float(w.y & 0xffff0000u)};
;                         b1 = (f32x4){__uint_as_float(w.z << 16), __uint_as_float(w.z & 0xffff0000u), __uint_as_float(w.w << 16), __uint_as_float(w.w & 0xffff0000u)}; }
;                     const f32x4 o0 = b0 + g[bj][0] * acc[ai][bj][m][0], o1 = b1 + g[bj][1] * acc[ai][bj][m][1];
;                     if (of) { *(f32x4*)(opf + off + bj * 128) = o0; *(f32x4*)(opf + off + bj * 128 + 4) = o1; }
;                     else { u32x4 w; w.x = pkbf(o0[0], o0[1]); w.y = pkbf(o0[2], o0[3]); w.z = pkbf(o1[0], o1[1]); w.w = pkbf(o1[2], o1[3]); *(u32x4*)(oph + off + bj * 128) = w; } } }
.LBB0_541:
	s_andn2_b64 vcc, exec, s[10:11]
	s_cbranch_vccnz .LBB0_670
	s_and_b64 vcc, exec, s[0:1]
	s_cbranch_vccnz .Lepi_wo_orig
	v_readlane_b32 s30, v240, 36
	s_nop 0
	s_cmp_eq_u32 s30, 0
	s_cbranch_scc1 .Lepi_wo_bf
	v_lshl_add_u32 v144, v172, 10, v170
	v_lshlrev_b32_e32 v145, 2, v144
	v_lshlrev_b32_e32 v144, 1, v144
	v_readfirstlane_b32 s8, v158
	v_readfirstlane_b32 s9, v159
	s_mov_b32 s10, s70
	s_mov_b32 s11, s71
	s_nop 4
	global_load_dwordx4 v[198:201], v145, s[8:9]
	global_load_dwordx4 v[202:205], v145, s[8:9] offset:16
	global_load_dwordx4 v[206:209], v145, s[8:9] offset:512
	global_load_dwordx4 v[210:213], v145, s[8:9] offset:528
	s_add_u32 s8, s8, 0x10000
	s_addc_u32 s9, s9, 0
	global_load_dwordx4 v[214:217], v145, s[8:9]
	global_load_dwordx4 v[218:221], v145, s[8:9] offset:16
	global_load_dwordx4 v[222:225], v145, s[8:9] offset:512
	global_load_dwordx4 v[188:191], v145, s[8:9] offset:528
	s_waitcnt vmcnt(6)
	v_pk_fma_f32 v[140:141], v[140:141], v[112:113], v[198:199]
	v_pk_fma_f32 v[142:143], v[142:143], v[114:115], v[200:201]
	v_pk_fma_f32 v[136:137], v[136:137], v[104:105], v[202:203]
	v_pk_fma_f32 v[138:139], v[138:139], v[106:107], v[204:205]
	s_add_u32 s8, s8, 0x10000
	s_addc_u32 s9, s9, 0
	global_load_dwordx4 v[198:201], v145, s[8:9]
	global_load_dwordx4 v[202:205], v145, s[8:9] offset:16
	v_cvt_pk_bf16_f32 v140, v140, v141
	v_cvt_pk_bf16_f32 v141, v142, v143
	v_cvt_pk_bf16_f32 v142, v136, v137
	v_cvt_pk_bf16_f32 v143, v138, v139
	global_store_dwordx4 v144, v[140:143], s[10:11]
	s_waitcnt vmcnt(7)
	v_pk_fma_f32 v[132:133], v[132:133], v[100:101], v[206:207]
	v_pk_fma_f32 v[134:135], v[134:135], v[102:103], v[208:209]
	v_pk_fma_f32 v[128:129], v[128:129], v[92:93], v[210:211]
	v_pk_fma_f32 v[130:131], v[130:131], v[94:95], v[212:213]
	global_load_dwordx4 v[206:209], v145, s[8:9] offset:512
	global_load_dwordx4 v[210:213], v145, s[8:9] offset:528
	v_cvt_pk_bf16_f32 v132, v132, v133
	v_cvt_pk_bf16_f32 v133, v134, v135
	v_cvt_pk_bf16_f32 v134, v128, v129
	v_cvt_pk_bf16_f32 v135, v130, v131
	global_store_dwordx4 v144, v[132:135], s[10:11] offset:256
	s_waitcnt vmcnt(8)
	v_pk_fma_f32 v[124:125], v[124:125], v[112:113], v[214:215]
	v_pk_fma_f32 v[126:127], v[126:127], v[114:115], v[216:217]
	v_pk_fma_f32 v[120:121], v[120:121], v[104:105], v[218:219]
	v_pk_fma_f32 v[122:123], v[122:123], v[106:107], v[220:221]
	s_add_u32 s8, s8, 0x10000
	s_addc_u32 s9, s9, 0
	global_load_dwordx4 v[214:217], v145, s[8:9]
	global_load_dwordx4 v[218:221], v145, s[8:9] offset:16
	s_add_u32 s10, s10, 0x8000
	s_addc_u32 s11, s11, 0
	v_cvt_pk_bf16_f32 v124, v124, v125
	v_cvt_pk_bf16_f32 v125, v126, v127
	v_cvt_pk_bf16_f32 v126, v120, v121
	v_cvt_pk_bf16_f32 v127, v122, v123
	global_store_dwordx4 v144, v[124:127], s[10:11]
	s_waitcnt vmcnt(9)
	v_pk_fma_f32 v[116:117], v[116:117], v[100:101], v[222:223]
	v_pk_fma_f32 v[118:119], v[118:119], v[102:103], v[224:225]
	v_pk_fma_f32 v[108:109], v[108:109], v[92:93], v[188:189]
	v_pk_fma_f32 v[110:111], v[110:111], v[94:95], v[190:191]
	global_load_dwordx4 v[222:225], v145, s[8:9] offset:512
	global_load_dwordx4 v[188:191], v145, s[8:9] offset:528
	v_cvt_pk_bf16_f32 v116, v116, v117
	v_cvt_pk_bf16_f32 v117, v118, v119
	v_cvt_pk_bf16_f32 v118, v108, v109
	v_cvt_pk_bf16_f32 v119, v110, v111
	global_store_dwordx4 v144, v[116:119], s[10:11] offset:256
	s_waitcnt vmcnt(10)
	v_pk_fma_f32 v[96:97], v[96:97], v[112:113], v[198:199]
	v_pk_fma_f32 v[98:99], v[98:99], v[114:115], v[200:201]
	v_pk_fma_f32 v[88:89], v[88:89], v[104:105], v[202:203]
	v_pk_fma_f32 v[90:91], v[90:91], v[106:107], v[204:205]
	s_add_u32 s8, s8, 0x50000
	s_addc_u32 s9, s9, 0
	global_load_dwordx4 v[198:201], v145, s[8:9]
	global_load_dwordx4 v[202:205], v145, s[8:9] offset:16
	s_add_u32 s10, s10, 0x8000
	s_addc_u32 s11, s11, 0
	v_cvt_pk_bf16_f32 v96, v96, v97
	v_cvt_pk_bf16_f32 v97, v98, v99
	v_cvt_pk_bf16_f32 v98, v88, v89
	v_cvt_pk_bf16_f32 v99, v90, v91
	global_store_dwordx4 v144, v[96:99], s[10:11]
	s_waitcnt vmcnt(10)
	v_pk_fma_f32 v[84:85], v[84:85], v[100:101], v[206:207]
	v_pk_fma_f32 v[86:87], v[86:87], v[102:103], v[208:209]
	v_pk_fma_f32 v[80:81], v[80:81], v[92:93], v[210:211]
	v_pk_fma_f32 v[82:83], v[82:83], v[94:95], v[212:213]
	global_load_dwordx4 v[206:209], v145, s[8:9] offset:512
	global_load_dwordx4 v[210:213], v145, s[8:9] offset:528
	v_cvt_pk_bf16_f32 v84, v84, v85
	v_cvt_pk_bf16_f32 v85, v86, v87
	v_cvt_pk_bf16_f32 v86, v80, v81
	v_cvt_pk_bf16_f32 v87, v82, v83
	global_store_dwordx4 v144, v[84:87], s[10:11] offset:256
	s_waitcnt vmcnt(10)
	v_pk_fma_f32 v[76:77], v[76:77], v[112:113], v[214:215]
	v_pk_fma_f32 v[78:79], v[78:79], v[114:115], v[216:217]
	v_pk_fma_f32 v[72:73], v[72:73], v[104:105], v[218:219]
	v_pk_fma_f32 v[74:75], v[74:75], v[106:107], v[220:221]
	s_add_u32 s8, s8, 0x10000
	s_addc_u32 s9, s9, 0
	global_load_dwordx4 v[214:217], v145, s[8:9]
	global_load_dwordx4 v[218:221], v145, s[8:9] offset:16
	s_add_u32 s10, s10, 0x8000
	s_addc_u32 s11, s11, 0
	v_cvt_pk_bf16_f32 v76, v76, v77
	v_cvt_pk_bf16_f32 v77, v78, v79
	v_cvt_pk_bf16_f32 v78, v72, v73
	v_cvt_pk_bf16_f32 v79, v74, v75
	global_store_dwordx4 v144, v[76:79], s[10:11]
	s_waitcnt vmcnt(10)
	v_pk_fma_f32 v[68:69], v[68:69], v[100:101], v[222:223]
	v_pk_fma_f32 v[70:71], v[70:71], v[102:103], v[224:225]
	v_pk_fma_f32 v[64:65], v[64:65], v[92:93], v[188:189]
	v_pk_fma_f32 v[66:67], v[66:67], v[94:95], v[190:191]
	global_load_dwordx4 v[222:225], v145, s[8:9] offset:512
	global_load_dwordx4 v[188:191], v145, s[8:9] offset:528
	v_cvt_pk_bf16_f32 v68, v68, v69
	v_cvt_pk_bf16_f32 v69, v70, v71
	v_cvt_pk_bf16_f32 v70, v64, v65
	v_cvt_pk_bf16_f32 v71, v66, v67
	global_store_dwordx4 v144, v[68:71], s[10:11] offset:256
	s_waitcnt vmcnt(10)
; __device__ __forceinline__ unsigned pkbf(float lo, float hi) { f32x2_t v = {lo, hi}; bf16x2_t b = __builtin_convertvector(v, bf16x2_t); return __builtin_bit_cast(unsigned, b); }
;     __device__ __forceinline__ void operator()(const f32x4 (&acc)[2][2][4][2], const pg8::Unit& u, int wr, int wc, int fr, int fq) const {
;     ...
;         for (int ai = 0; ai < 2; ++ai)
; #pragma unroll
;             for (int m = 0; m < 4; ++m) { const size_t off = (size_t)(row0 + ai * 128 + m * 16) * DM + col0;
; #pragma unroll
;                 for (int bj = 0; bj < 2; ++bj) {
;                     f32x4 b0, b1;
;                     if (bf) { b0 = *(const f32x4*)(bpf + off + bj * 128); b1 = *(const f32x4*)(bpf + off + bj * 128 + 4); }
;                     else { const u32x4 w = *(const u32x4*)(bph + off + bj * 128);
;                         b0 = (f32x4){__uint_as_float(w.x << 16), __uint_as_float(w.x & 0xffff0000u), __uint_as_float(w.y << 16), __uint_as_float(w.y & 0xffff0000u)};
;                         b1 = (f32x4){__uint_as_float(w.z << 16), __uint_as_float(w.z & 0xffff0000u), __uint_as_float(w.w << 16), __uint_as_float(w.w & 0xffff0000u)}; }
;                     const f32x4 o0 = b0 + g[bj][0] * acc[ai][bj][m][0], o1 = b1 + g[bj][1] * acc[ai][bj][m][1];
;                     if (of) { *(f32x4*)(opf + off + bj * 128) = o0; *(f32x4*)(opf + off + bj * 128 + 4) = o1; }
;                     else { u32x4 w; w.x = pkbf(o0[0], o0[1]); w.y = pkbf(o0[2], o0[3]); w.z = pkbf(o1[0], o1[1]); w.w = pkbf(o1[2], o1[3]); *(u32x4*)(oph + off + bj * 128) = w; } } }
	v_pk_fma_f32 v[60:61], v[60:61], v[112:113], v[198:199]
	v_pk_fma_f32 v[62:63], v[62:63], v[114:115], v[200:201]
	v_pk_fma_f32 v[56:57], v[56:57], v[104:105], v[202:203]
	v_pk_fma_f32 v[58:59], v[58:59], v[106:107], v[204:205]
	s_add_u32 s8, s8, 0x10000
	s_addc_u32 s9, s9, 0
	global_load_dwordx4 v[198:201], v145, s[8:9]
	global_load_dwordx4 v[202:205], v145, s[8:9] offset:16
	s_add_u32 s10, s10, 0x28000
	s_addc_u32 s11, s11, 0
	v_cvt_pk_bf16_f32 v60, v60, v61
	v_cvt_pk_bf16_f32 v61, v62, v63
	v_cvt_pk_bf16_f32 v62, v56, v57
	v_cvt_pk_bf16_f32 v63, v58, v59
	global_store_dwordx4 v144, v[60:63], s[10:11]
	s_waitcnt vmcnt(10)
	v_pk_fma_f32 v[52:53], v[52:53], v[100:101], v[206:207]
	v_pk_fma_f32 v[54:55], v[54:55], v[102:103], v[208:209]
	v_pk_fma_f32 v[48:49], v[48:49], v[92:93], v[210:211]
	v_pk_fma_f32 v[50:51], v[50:51], v[94:95], v[212:213]
	global_load_dwordx4 v[206:209], v145, s[8:9] offset:512
	global_load_dwordx4 v[210:213], v145, s[8:9] offset:528
	v_cvt_pk_bf16_f32 v52, v52, v53
	v_cvt_pk_bf16_f32 v53, v54, v55
	v_cvt_pk_bf16_f32 v54, v48, v49
	v_cvt_pk_bf16_f32 v55, v50, v51
	global_store_dwordx4 v144, v[52:55], s[10:11] offset:256
	s_waitcnt vmcnt(10)
	v_pk_fma_f32 v[44:45], v[44:45], v[112:113], v[214:215]
	v_pk_fma_f32 v[46:47], v[46:47], v[114:115], v[216:217]
	v_pk_fma_f32 v[40:41], v[40:41], v[104:105], v[218:219]
	v_pk_fma_f32 v[42:43], v[42:43], v[106:107], v[220:221]
	s_add_u32 s8, s8, 0x10000
	s_addc_u32 s9, s9, 0
	global_load_dwordx4 v[214:217], v145, s[8:9]
	global_load_dwordx4 v[218:221], v145, s[8:9] offset:16
	s_add_u32 s10, s10, 0x8000
	s_addc_u32 s11, s11, 0
	v_cvt_pk_bf16_f32 v44, v44, v45
	v_cvt_pk_bf16_f32 v45, v46, v47
	v_cvt_pk_bf16_f32 v46, v40, v41
	v_cvt_pk_bf16_f32 v47, v42, v43
	global_store_dwordx4 v144, v[44:47], s[10:11]
	s_waitcnt vmcnt(10)
	v_pk_fma_f32 v[36:37], v[36:37], v[100:101], v[222:223]
	v_pk_fma_f32 v[38:39], v[38:39], v[102:103], v[224:225]
	v_pk_fma_f32 v[32:33], v[32:33], v[92:93], v[188:189]
	v_pk_fma_f32 v[34:35], v[34:35], v[94:95], v[190:191]
	global_load_dwordx4 v[222:225], v145, s[8:9] offset:512
	global_load_dwordx4 v[188:191], v145, s[8:9] offset:528
	v_cvt_pk_bf16_f32 v36, v36, v37
	v_cvt_pk_bf16_f32 v37, v38, v39
	v_cvt_pk_bf16_f32 v38, v32, v33
	v_cvt_pk_bf16_f32 v39, v34, v35
	global_store_dwordx4 v144, v[36:39], s[10:11] offset:256
	s_waitcnt vmcnt(10)
	v_pk_fma_f32 v[28:29], v[28:29], v[112:113], v[198:199]
	v_pk_fma_f32 v[30:31], v[30:31], v[114:115], v[200:201]
	v_pk_fma_f32 v[24:25], v[24:25], v[104:105], v[202:203]
	v_pk_fma_f32 v[26:27], v[26:27], v[106:107], v[204:205]
	s_add_u32 s10, s10, 0x8000
	s_addc_u32 s11, s11, 0
	v_cvt_pk_bf16_f32 v28, v28, v29
	v_cvt_pk_bf16_f32 v29, v30, v31
	v_cvt_pk_bf16_f32 v30, v24, v25
	v_cvt_pk_bf16_f32 v31, v26, v27
	global_store_dwordx4 v144, v[28:31], s[10:11]
	s_waitcnt vmcnt(8)
	v_pk_fma_f32 v[20:21], v[20:21], v[100:101], v[206:207]
	v_pk_fma_f32 v[22:23], v[22:23], v[102:103], v[208:209]
	v_pk_fma_f32 v[16:17], v[16:17], v[92:93], v[210:211]
	v_pk_fma_f32 v[18:19], v[18:19], v[94:95], v[212:213]
	v_cvt_pk_bf16_f32 v20, v20, v21
	v_cvt_pk_bf16_f32 v21, v22, v23
	v_cvt_pk_bf16_f32 v22, v16, v17
	v_cvt_pk_bf16_f32 v23, v18, v19
	global_store_dwordx4 v144, v[20:23], s[10:11] offset:256
	s_waitcnt vmcnt(6)
	v_pk_fma_f32 v[12:13], v[12:13], v[112:113], v[214:215]
	v_pk_fma_f32 v[14:15], v[14:15], v[114:115], v[216:217]
	v_pk_fma_f32 v[8:9], v[8:9], v[104:105], v[218:219]
	v_pk_fma_f32 v[10:11], v[10:11], v[106:107], v[220:221]
	s_add_u32 s10, s10, 0x8000
	s_addc_u32 s11, s11, 0
	v_cvt_pk_bf16_f32 v12, v12, v13
	v_cvt_pk_bf16_f32 v13, v14, v15
	v_cvt_pk_bf16_f32 v14, v8, v9
	v_cvt_pk_bf16_f32 v15, v10, v11
	global_store_dwordx4 v144, v[12:15], s[10:11]
	s_waitcnt vmcnt(4)
	v_pk_fma_f32 v[4:5], v[4:5], v[100:101], v[222:223]
	v_pk_fma_f32 v[6:7], v[6:7], v[102:103], v[224:225]
	v_pk_fma_f32 v[0:1], v[0:1], v[92:93], v[188:189]
	v_pk_fma_f32 v[2:3], v[2:3], v[94:95], v[190:191]
	v_cvt_pk_bf16_f32 v4, v4, v5
	v_cvt_pk_bf16_f32 v5, v6, v7
	v_cvt_pk_bf16_f32 v6, v0, v1
	v_cvt_pk_bf16_f32 v7, v2, v3
	global_store_dwordx4 v144, v[4:7], s[10:11] offset:256
	s_branch .LBB0_670
.Lepi_wo_bf:
	v_lshl_add_u32 v144, v172, 10, v170
	v_lshlrev_b32_e32 v145, 2, v144
	v_lshlrev_b32_e32 v144, 1, v144
	v_readfirstlane_b32 s8, v158
	v_readfirstlane_b32 s9, v159
	s_mov_b32 s10, s70
	s_mov_b32 s11, s71
	s_nop 4
	global_load_dwordx4 v[198:201], v144, s[8:9]
	global_load_dwordx4 v[202:205], v144, s[8:9] offset:256
	s_add_u32 s8, s8, 0x8000
	s_addc_u32 s9, s9, 0
	global_load_dwordx4 v[206:209], v144, s[8:9]
	global_load_dwordx4 v[210:213], v144, s[8:9] offset:256
	s_add_u32 s8, s8, 0x8000
	s_addc_u32 s9, s9, 0
	global_load_dwordx4 v[214:217], v144, s[8:9]
	global_load_dwordx4 v[218:221], v144, s[8:9] offset:256
	s_add_u32 s8, s8, 0x8000
	s_addc_u32 s9, s9, 0
	global_load_dwordx4 v[222:225], v144, s[8:9]
	global_load_dwordx4 v[188:191], v144, s[8:9] offset:256
	s_waitcnt vmcnt(7)
	v_lshlrev_b32_e32 v176, 16, v198
	v_and_b32_e32 v177, 0xffff0000, v198
	v_lshlrev_b32_e32 v178, 16, v199
	v_and_b32_e32 v179, 0xffff0000, v199
	v_lshlrev_b32_e32 v180, 16, v200
	v_and_b32_e32 v181, 0xffff0000, v200
	v_lshlrev_b32_e32 v182, 16, v201
	v_and_b32_e32 v183, 0xffff0000, v201
	v_pk_fma_f32 v[140:141], v[140:141], v[112:113], v[176:177]
	v_pk_fma_f32 v[142:143], v[142:143], v[114:115], v[178:179]
	v_pk_fma_f32 v[136:137], v[136:137], v[104:105], v[180:181]
	v_pk_fma_f32 v[138:139], v[138:139], v[106:107], v[182:183]
	s_add_u32 s8, s8, 0x28000
	s_addc_u32 s9, s9, 0
	global_load_dwordx4 v[198:201], v144, s[8:9]
	v_cvt_pk_bf16_f32 v140, v140, v141
	v_cvt_pk_bf16_f32 v141, v142, v143
	v_cvt_pk_bf16_f32 v142, v136, v137
	v_cvt_pk_bf16_f32 v143, v138, v139
	global_store_dwordx4 v144, v[140:143], s[10:11]
	s_waitcnt vmcnt(8)
; __device__ __forceinline__ unsigned pkbf(float lo, float hi) { f32x2_t v = {lo, hi}; bf16x2_t b = __builtin_convertvector(v, bf16x2_t); return __builtin_bit_cast(unsigned, b); }
;     __device__ __forceinline__ void operator()(const f32x4 (&acc)[2][2][4][2], const pg8::Unit& u, int wr, int wc, int fr, int fq) const {
;     ...
;         for (int ai = 0; ai < 2; ++ai)
; #pragma unroll
;             for (int m = 0; m < 4; ++m) { const size_t off = (size_t)(row0 + ai * 128 + m * 16) * DM + col0;
; #pragma unroll
;                 for (int bj = 0; bj < 2; ++bj) {
;                     f32x4 b0, b1;
;                     if (bf) { b0 = *(const f32x4*)(bpf + off + bj * 128); b1 = *(const f32x4*)(bpf + off + bj * 128 + 4); }
;                     else { const u32x4 w = *(const u32x4*)(bph + off + bj * 128);
;                         b0 = (f32x4){__uint_as_float(w.x << 16), __uint_as_float(w.x & 0xffff0000u), __uint_as_float(w.y << 16), __uint_as_float(w.y & 0xffff0000u)};
;                         b1 = (f32x4){__uint_as_float(w.z << 16), __uint_as_float(w.z & 0xffff0000u), __uint_as_float(w.w << 16), __uint_as_float(w.w & 0xffff0000u)}; }
;                     const f32x4 o0 = b0 + g[bj][0] * acc[ai][bj][m][0], o1 = b1 + g[bj][1] * acc[ai][bj][m][1];
;                     if (of) { *(f32x4*)(opf + off + bj * 128) = o0; *(f32x4*)(opf + off + bj * 128 + 4) = o1; }
;                     else { u32x4 w; w.x = pkbf(o0[0], o0[1]); w.y = pkbf(o0[2], o0[3]); w.z = pkbf(o1[0], o1[1]); w.w = pkbf(o1[2], o1[3]); *(u32x4*)(oph + off + bj * 128) = w; } } }
	v_lshlrev_b32_e32 v176, 16, v202
	v_and_b32_e32 v177, 0xffff0000, v202
	v_lshlrev_b32_e32 v178, 16, v203
	v_and_b32_e32 v179, 0xffff0000, v203
	v_lshlrev_b32_e32 v180, 16, v204
	v_and_b32_e32 v181, 0xffff0000, v204
	v_lshlrev_b32_e32 v182, 16, v205
	v_and_b32_e32 v183, 0xffff0000, v205
	v_pk_fma_f32 v[132:133], v[132:133], v[100:101], v[176:177]
	v_pk_fma_f32 v[134:135], v[134:135], v[102:103], v[178:179]
	v_pk_fma_f32 v[128:129], v[128:129], v[92:93], v[180:181]
	v_pk_fma_f32 v[130:131], v[130:131], v[94:95], v[182:183]
	global_load_dwordx4 v[202:205], v144, s[8:9] offset:256
	v_cvt_pk_bf16_f32 v132, v132, v133
	v_cvt_pk_bf16_f32 v133, v134, v135
	v_cvt_pk_bf16_f32 v134, v128, v129
	v_cvt_pk_bf16_f32 v135, v130, v131
	global_store_dwordx4 v144, v[132:135], s[10:11] offset:256
	s_waitcnt vmcnt(9)
	v_lshlrev_b32_e32 v176, 16, v206
	v_and_b32_e32 v177, 0xffff0000, v206
	v_lshlrev_b32_e32 v178, 16, v207
	v_and_b32_e32 v179, 0xffff0000, v207
	v_lshlrev_b32_e32 v180, 16, v208
	v_and_b32_e32 v181, 0xffff0000, v208
	v_lshlrev_b32_e32 v182, 16, v209
	v_and_b32_e32 v183, 0xffff0000, v209
	v_pk_fma_f32 v[124:125], v[124:125], v[112:113], v[176:177]
	v_pk_fma_f32 v[126:127], v[126:127], v[114:115], v[178:179]
	v_pk_fma_f32 v[120:121], v[120:121], v[104:105], v[180:181]
	v_pk_fma_f32 v[122:123], v[122:123], v[106:107], v[182:183]
	s_add_u32 s8, s8, 0x8000
	s_addc_u32 s9, s9, 0
	global_load_dwordx4 v[206:209], v144, s[8:9]
	s_add_u32 s10, s10, 0x8000
	s_addc_u32 s11, s11, 0
	v_cvt_pk_bf16_f32 v124, v124, v125
	v_cvt_pk_bf16_f32 v125, v126, v127
	v_cvt_pk_bf16_f32 v126, v120, v121
	v_cvt_pk_bf16_f32 v127, v122, v123
	global_store_dwordx4 v144, v[124:127], s[10:11]
	s_waitcnt vmcnt(10)
	v_lshlrev_b32_e32 v176, 16, v210
	v_and_b32_e32 v177, 0xffff0000, v210
	v_lshlrev_b32_e32 v178, 16, v211
	v_and_b32_e32 v179, 0xffff0000, v211
	v_lshlrev_b32_e32 v180, 16, v212
	v_and_b32_e32 v181, 0xffff0000, v212
	v_lshlrev_b32_e32 v182, 16, v213
	v_and_b32_e32 v183, 0xffff0000, v213
	v_pk_fma_f32 v[116:117], v[116:117], v[100:101], v[176:177]
	v_pk_fma_f32 v[118:119], v[118:119], v[102:103], v[178:179]
	v_pk_fma_f32 v[108:109], v[108:109], v[92:93], v[180:181]
	v_pk_fma_f32 v[110:111], v[110:111], v[94:95], v[182:183]
	global_load_dwordx4 v[210:213], v144, s[8:9] offset:256
	v_cvt_pk_bf16_f32 v116, v116, v117
	v_cvt_pk_bf16_f32 v117, v118, v119
	v_cvt_pk_bf16_f32 v118, v108, v109
	v_cvt_pk_bf16_f32 v119, v110, v111
	global_store_dwordx4 v144, v[116:119], s[10:11] offset:256
	s_waitcnt vmcnt(11)
	v_lshlrev_b32_e32 v176, 16, v214
	v_and_b32_e32 v177, 0xffff0000, v214
	v_lshlrev_b32_e32 v178, 16, v215
	v_and_b32_e32 v179, 0xffff0000, v215
	v_lshlrev_b32_e32 v180, 16, v216
	v_and_b32_e32 v181, 0xffff0000, v216
	v_lshlrev_b32_e32 v182, 16, v217
	v_and_b32_e32 v183, 0xffff0000, v217
	v_pk_fma_f32 v[96:97], v[96:97], v[112:113], v[176:177]
	v_pk_fma_f32 v[98:99], v[98:99], v[114:115], v[178:179]
	v_pk_fma_f32 v[88:89], v[88:89], v[104:105], v[180:181]
	v_pk_fma_f32 v[90:91], v[90:91], v[106:107], v[182:183]
	s_add_u32 s8, s8, 0x8000
	s_addc_u32 s9, s9, 0
	global_load_dwordx4 v[214:217], v144, s[8:9]
	s_add_u32 s10, s10, 0x8000
	s_addc_u32 s11, s11, 0
	v_cvt_pk_bf16_f32 v96, v96, v97
	v_cvt_pk_bf16_f32 v97, v98, v99
	v_cvt_pk_bf16_f32 v98, v88, v89
	v_cvt_pk_bf16_f32 v99, v90, v91
	global_store_dwordx4 v144, v[96:99], s[10:11]
	s_waitcnt vmcnt(12)
	v_lshlrev_b32_e32 v176, 16, v218
	v_and_b32_e32 v177, 0xffff0000, v218
	v_lshlrev_b32_e32 v178, 16, v219
	v_and_b32_e32 v179, 0xffff0000, v219
	v_lshlrev_b32_e32 v180, 16, v220
	v_and_b32_e32 v181, 0xffff0000, v220
	v_lshlrev_b32_e32 v182, 16, v221
	v_and_b32_e32 v183, 0xffff0000, v221
	v_pk_fma_f32 v[84:85], v[84:85], v[100:101], v[176:177]
	v_pk_fma_f32 v[86:87], v[86:87], v[102:103], v[178:179]
	v_pk_fma_f32 v[80:81], v[80:81], v[92:93], v[180:181]
	v_pk_fma_f32 v[82:83], v[82:83], v[94:95], v[182:183]
	global_load_dwordx4 v[218:221], v144, s[8:9] offset:256
	v_cvt_pk_bf16_f32 v84, v84, v85
	v_cvt_pk_bf16_f32 v85, v86, v87
	v_cvt_pk_bf16_f32 v86, v80, v81
	v_cvt_pk_bf16_f32 v87, v82, v83
	global_store_dwordx4 v144, v[84:87], s[10:11] offset:256
	s_waitcnt vmcnt(13)
	v_lshlrev_b32_e32 v176, 16, v222
	v_and_b32_e32 v177, 0xffff0000, v222
	v_lshlrev_b32_e32 v178, 16, v223
	v_and_b32_e32 v179, 0xffff0000, v223
	v_lshlrev_b32_e32 v180, 16, v224
	v_and_b32_e32 v181, 0xffff0000, v224
	v_lshlrev_b32_e32 v182, 16, v225
	v_and_b32_e32 v183, 0xffff0000, v225
	v_pk_fma_f32 v[76:77], v[76:77], v[112:113], v[176:177]
	v_pk_fma_f32 v[78:79], v[78:79], v[114:115], v[178:179]
	v_pk_fma_f32 v[72:73], v[72:73], v[104:105], v[180:181]
	v_pk_fma_f32 v[74:75], v[74:75], v[106:107], v[182:183]
	s_add_u32 s8, s8, 0x8000
	s_addc_u32 s9, s9, 0
	global_load_dwordx4 v[222:225], v144, s[8:9]
	s_add_u32 s10, s10, 0x8000
	s_addc_u32 s11, s11, 0
	v_cvt_pk_bf16_f32 v76, v76, v77
	v_cvt_pk_bf16_f32 v77, v78, v79
	v_cvt_pk_bf16_f32 v78, v72, v73
	v_cvt_pk_bf16_f32 v79, v74, v75
	global_store_dwordx4 v144, v[76:79], s[10:11]
	s_waitcnt vmcnt(14)
	v_lshlrev_b32_e32 v176, 16, v188
	v_and_b32_e32 v177, 0xffff0000, v188
	v_lshlrev_b32_e32 v178, 16, v189
	v_and_b32_e32 v179, 0xffff0000, v189
	v_lshlrev_b32_e32 v180, 16, v190
	v_and_b32_e32 v181, 0xffff0000, v190
	v_lshlrev_b32_e32 v182, 16, v191
	v_and_b32_e32 v183, 0xffff0000, v191
	v_pk_fma_f32 v[68:69], v[68:69], v[100:101], v[176:177]
	v_pk_fma_f32 v[70:71], v[70:71], v[102:103], v[178:179]
	v_pk_fma_f32 v[64:65], v[64:65], v[92:93], v[180:181]
	v_pk_fma_f32 v[66:67], v[66:67], v[94:95], v[182:183]
	global_load_dwordx4 v[188:191], v144, s[8:9] offset:256
	v_cvt_pk_bf16_f32 v68, v68, v69
	v_cvt_pk_bf16_f32 v69, v70, v71
	v_cvt_pk_bf16_f32 v70, v64, v65
	v_cvt_pk_bf16_f32 v71, v66, v67
	global_store_dwordx4 v144, v[68:71], s[10:11] offset:256
	s_waitcnt vmcnt(15)
; __device__ __forceinline__ unsigned pkbf(float lo, float hi) { f32x2_t v = {lo, hi}; bf16x2_t b = __builtin_convertvector(v, bf16x2_t); return __builtin_bit_cast(unsigned, b); }
;     __device__ __forceinline__ void operator()(const f32x4 (&acc)[2][2][4][2], const pg8::Unit& u, int wr, int wc, int fr, int fq) const {
;     ...
;         for (int ai = 0; ai < 2; ++ai)
; #pragma unroll
;             for (int m = 0; m < 4; ++m) { const size_t off = (size_t)(row0 + ai * 128 + m * 16) * DM + col0;
; #pragma unroll
;                 for (int bj = 0; bj < 2; ++bj) {
;                     f32x4 b0, b1;
;                     if (bf) { b0 = *(const f32x4*)(bpf + off + bj * 128); b1 = *(const f32x4*)(bpf + off + bj * 128 + 4); }
;                     else { const u32x4 w = *(const u32x4*)(bph + off + bj * 128);
;                         b0 = (f32x4){__uint_as_float(w.x << 16), __uint_as_float(w.x & 0xffff0000u), __uint_as_float(w.y << 16), __uint_as_float(w.y & 0xffff0000u)};
;                         b1 = (f32x4){__uint_as_float(w.z << 16), __uint_as_float(w.z & 0xffff0000u), __uint_as_float(w.w << 16), __uint_as_float(w.w & 0xffff0000u)}; }
;                     const f32x4 o0 = b0 + g[bj][0] * acc[ai][bj][m][0], o1 = b1 + g[bj][1] * acc[ai][bj][m][1];
;                     if (of) { *(f32x4*)(opf + off + bj * 128) = o0; *(f32x4*)(opf + off + bj * 128 + 4) = o1; }
;                     else { u32x4 w; w.x = pkbf(o0[0], o0[1]); w.y = pkbf(o0[2], o0[3]); w.z = pkbf(o1[0], o1[1]); w.w = pkbf(o1[2], o1[3]); *(u32x4*)(oph + off + bj * 128) = w; } } }
	v_lshlrev_b32_e32 v176, 16, v198
	v_and_b32_e32 v177, 0xffff0000, v198
	v_lshlrev_b32_e32 v178, 16, v199
	v_and_b32_e32 v179, 0xffff0000, v199
	v_lshlrev_b32_e32 v180, 16, v200
	v_and_b32_e32 v181, 0xffff0000, v200
	v_lshlrev_b32_e32 v182, 16, v201
	v_and_b32_e32 v183, 0xffff0000, v201
	v_pk_fma_f32 v[60:61], v[60:61], v[112:113], v[176:177]
	v_pk_fma_f32 v[62:63], v[62:63], v[114:115], v[178:179]
	v_pk_fma_f32 v[56:57], v[56:57], v[104:105], v[180:181]
	v_pk_fma_f32 v[58:59], v[58:59], v[106:107], v[182:183]
	s_add_u32 s10, s10, 0x28000
	s_addc_u32 s11, s11, 0
	v_cvt_pk_bf16_f32 v60, v60, v61
	v_cvt_pk_bf16_f32 v61, v62, v63
	v_cvt_pk_bf16_f32 v62, v56, v57
	v_cvt_pk_bf16_f32 v63, v58, v59
	global_store_dwordx4 v144, v[60:63], s[10:11]
	s_waitcnt vmcnt(14)
	v_lshlrev_b32_e32 v176, 16, v202
	v_and_b32_e32 v177, 0xffff0000, v202
	v_lshlrev_b32_e32 v178, 16, v203
	v_and_b32_e32 v179, 0xffff0000, v203
	v_lshlrev_b32_e32 v180, 16, v204
	v_and_b32_e32 v181, 0xffff0000, v204
	v_lshlrev_b32_e32 v182, 16, v205
	v_and_b32_e32 v183, 0xffff0000, v205
	v_pk_fma_f32 v[52:53], v[52:53], v[100:101], v[176:177]
	v_pk_fma_f32 v[54:55], v[54:55], v[102:103], v[178:179]
	v_pk_fma_f32 v[48:49], v[48:49], v[92:93], v[180:181]
	v_pk_fma_f32 v[50:51], v[50:51], v[94:95], v[182:183]
	v_cvt_pk_bf16_f32 v52, v52, v53
	v_cvt_pk_bf16_f32 v53, v54, v55
	v_cvt_pk_bf16_f32 v54, v48, v49
	v_cvt_pk_bf16_f32 v55, v50, v51
	global_store_dwordx4 v144, v[52:55], s[10:11] offset:256
	s_waitcnt vmcnt(13)
	v_lshlrev_b32_e32 v176, 16, v206
	v_and_b32_e32 v177, 0xffff0000, v206
	v_lshlrev_b32_e32 v178, 16, v207
	v_and_b32_e32 v179, 0xffff0000, v207
	v_lshlrev_b32_e32 v180, 16, v208
	v_and_b32_e32 v181, 0xffff0000, v208
	v_lshlrev_b32_e32 v182, 16, v209
	v_and_b32_e32 v183, 0xffff0000, v209
	v_pk_fma_f32 v[44:45], v[44:45], v[112:113], v[176:177]
	v_pk_fma_f32 v[46:47], v[46:47], v[114:115], v[178:179]
	v_pk_fma_f32 v[40:41], v[40:41], v[104:105], v[180:181]
	v_pk_fma_f32 v[42:43], v[42:43], v[106:107], v[182:183]
	s_add_u32 s10, s10, 0x8000
	s_addc_u32 s11, s11, 0
	v_cvt_pk_bf16_f32 v44, v44, v45
	v_cvt_pk_bf16_f32 v45, v46, v47
	v_cvt_pk_bf16_f32 v46, v40, v41
	v_cvt_pk_bf16_f32 v47, v42, v43
	global_store_dwordx4 v144, v[44:47], s[10:11]
	s_waitcnt vmcnt(12)
	v_lshlrev_b32_e32 v176, 16, v210
	v_and_b32_e32 v177, 0xffff0000, v210
	v_lshlrev_b32_e32 v178, 16, v211
	v_and_b32_e32 v179, 0xffff0000, v211
	v_lshlrev_b32_e32 v180, 16, v212
	v_and_b32_e32 v181, 0xffff0000, v212
	v_lshlrev_b32_e32 v182, 16, v213
	v_and_b32_e32 v183, 0xffff0000, v213
	v_pk_fma_f32 v[36:37], v[36:37], v[100:101], v[176:177]
	v_pk_fma_f32 v[38:39], v[38:39], v[102:103], v[178:179]
	v_pk_fma_f32 v[32:33], v[32:33], v[92:93], v[180:181]
	v_pk_fma_f32 v[34:35], v[34:35], v[94:95], v[182:183]
	v_cvt_pk_bf16_f32 v36, v36, v37
	v_cvt_pk_bf16_f32 v37, v38, v39
	v_cvt_pk_bf16_f32 v38, v32, v33
	v_cvt_pk_bf16_f32 v39, v34, v35
	global_store_dwordx4 v144, v[36:39], s[10:11] offset:256
	s_waitcnt vmcnt(11)
	v_lshlrev_b32_e32 v176, 16, v214
	v_and_b32_e32 v177, 0xffff0000, v214
	v_lshlrev_b32_e32 v178, 16, v215
	v_and_b32_e32 v179, 0xffff0000, v215
	v_lshlrev_b32_e32 v180, 16, v216
	v_and_b32_e32 v181, 0xffff0000, v216
	v_lshlrev_b32_e32 v182, 16, v217
	v_and_b32_e32 v183, 0xffff0000, v217
	v_pk_fma_f32 v[28:29], v[28:29], v[112:113], v[176:177]
	v_pk_fma_f32 v[30:31], v[30:31], v[114:115], v[178:179]
	v_pk_fma_f32 v[24:25], v[24:25], v[104:105], v[180:181]
	v_pk_fma_f32 v[26:27], v[26:27], v[106:107], v[182:183]
	s_add_u32 s10, s10, 0x8000
	s_addc_u32 s11, s11, 0
	v_cvt_pk_bf16_f32 v28, v28, v29
	v_cvt_pk_bf16_f32 v29, v30, v31
	v_cvt_pk_bf16_f32 v30, v24, v25
	v_cvt_pk_bf16_f32 v31, v26, v27
	global_store_dwordx4 v144, v[28:31], s[10:11]
	s_waitcnt vmcnt(10)
	v_lshlrev_b32_e32 v176, 16, v218
	v_and_b32_e32 v177, 0xffff0000, v218
	v_lshlrev_b32_e32 v178, 16, v219
	v_and_b32_e32 v179, 0xffff0000, v219
	v_lshlrev_b32_e32 v180, 16, v220
	v_and_b32_e32 v181, 0xffff0000, v220
	v_lshlrev_b32_e32 v182, 16, v221
	v_and_b32_e32 v183, 0xffff0000, v221
	v_pk_fma_f32 v[20:21], v[20:21], v[100:101], v[176:177]
	v_pk_fma_f32 v[22:23], v[22:23], v[102:103], v[178:179]
	v_pk_fma_f32 v[16:17], v[16:17], v[92:93], v[180:181]
	v_pk_fma_f32 v[18:19], v[18:19], v[94:95], v[182:183]
	v_cvt_pk_bf16_f32 v20, v20, v21
	v_cvt_pk_bf16_f32 v21, v22, v23
	v_cvt_pk_bf16_f32 v22, v16, v17
	v_cvt_pk_bf16_f32 v23, v18, v19
	global_store_dwordx4 v144, v[20:23], s[10:11] offset:256
	s_waitcnt vmcnt(9)
	v_lshlrev_b32_e32 v176, 16, v222
	v_and_b32_e32 v177, 0xffff0000, v222
	v_lshlrev_b32_e32 v178, 16, v223
	v_and_b32_e32 v179, 0xffff0000, v223
	v_lshlrev_b32_e32 v180, 16, v224
	v_and_b32_e32 v181, 0xffff0000, v224
	v_lshlrev_b32_e32 v182, 16, v225
	v_and_b32_e32 v183, 0xffff0000, v225
	v_pk_fma_f32 v[12:13], v[12:13], v[112:113], v[176:177]
	v_pk_fma_f32 v[14:15], v[14:15], v[114:115], v[178:179]
	v_pk_fma_f32 v[8:9], v[8:9], v[104:105], v[180:181]
	v_pk_fma_f32 v[10:11], v[10:11], v[106:107], v[182:183]
	s_add_u32 s10, s10, 0x8000
	s_addc_u32 s11, s11, 0
	v_cvt_pk_bf16_f32 v12, v12, v13
	v_cvt_pk_bf16_f32 v13, v14, v15
	v_cvt_pk_bf16_f32 v14, v8, v9
	v_cvt_pk_bf16_f32 v15, v10, v11
	global_store_dwordx4 v144, v[12:15], s[10:11]
	s_waitcnt vmcnt(8)
	v_lshlrev_b32_e32 v176, 16, v188
	v_and_b32_e32 v177, 0xffff0000, v188
	v_lshlrev_b32_e32 v178, 16, v189
	v_and_b32_e32 v179, 0xffff0000, v189
	v_lshlrev_b32_e32 v180, 16, v190
	v_and_b32_e32 v181, 0xffff0000, v190
	v_lshlrev_b32_e32 v182, 16, v191
	v_and_b32_e32 v183, 0xffff0000, v191
	v_pk_fma_f32 v[4:5], v[4:5], v[100:101], v[176:177]
	v_pk_fma_f32 v[6:7], v[6:7], v[102:103], v[178:179]
	v_pk_fma_f32 v[0:1], v[0:1], v[92:93], v[180:181]
	v_pk_fma_f32 v[2:3], v[2:3], v[94:95], v[182:183]
	v_cvt_pk_bf16_f32 v4, v4, v5
	v_cvt_pk_bf16_f32 v5, v6, v7
	v_cvt_pk_bf16_f32 v6, v0, v1
	v_cvt_pk_bf16_f32 v7, v2, v3
	global_store_dwordx4 v144, v[4:7], s[10:11] offset:256
	s_branch .LBB0_670
.Lepi_wo_orig:
	v_readlane_b32 s8, v240, 36
	v_readlane_b32 s9, v240, 37
	v_lshlrev_b64 v[144:145], 10, v[172:173]
	s_nor_b64 s[10:11], s[8:9], s[0:1]
	v_lshl_add_u64 v[182:183], v[144:145], 0, v[170:171]
	s_waitcnt vmcnt(0)
	v_lshl_add_u64 v[178:179], v[182:183], 1, v[158:159]
	s_mov_b64 s[8:9], -1
	s_and_b64 vcc, exec, s[10:11]
	s_cbranch_vccz .LBB0_544
	flat_load_dwordx4 v[144:147], v[178:179]
	s_mov_b64 s[8:9], 0
	s_waitcnt vmcnt(0) lgkmcnt(0)
	v_lshlrev_b32_e32 v148, 16, v144
	v_and_b32_e32 v149, 0xffff0000, v144
	v_lshlrev_b32_e32 v150, 16, v145
	v_and_b32_e32 v151, 0xffff0000, v145
	v_lshlrev_b32_e32 v144, 16, v146
	v_and_b32_e32 v145, 0xffff0000, v146
	v_lshlrev_b32_e32 v146, 16, v147
	v_and_b32_e32 v147, 0xffff0000, v147

; __device__ __forceinline__ unsigned pkbf(float lo, float hi) { f32x2_t v = {lo, hi}; bf16x2_t b = __builtin_convertvector(v, bf16x2_t); return __builtin_bit_cast(unsigned, b); }
;     __device__ __forceinline__ void operator()(const f32x4 (&acc)[2][2][4][2], const pg8::Unit& u, int wr, int wc, int fr, int fq) const {
;     ...
;         const bool bf = isctx || base_f32, of = isctx || out_f32;
;         const float* bpf = isctx ? base_ctx : (const float*)base_lat; float* opf = isctx ? out_ctx : (float*)out_lat;
;         const bf16_t* bph = (const bf16_t*)base_lat; bf16_t* oph = (bf16_t*)out_lat;
; #pragma unroll
;         for (int ai = 0; ai < 2; ++ai)
; #pragma unroll
;             for (int m = 0; m < 4; ++m) { const size_t off = (size_t)(row0 + ai * 128 + m * 16) * DM + col0;
; #pragma unroll
;                 for (int bj = 0; bj < 2; ++bj) {
;                     f32x4 b0, b1;
;                     if (bf) { b0 = *(const f32x4*)(bpf + off + bj * 128); b1 = *(const f32x4*)(bpf + off + bj * 128 + 4); }
;                     else { const u32x4 w = *(const u32x4*)(bph + off + bj * 128);
;                         b0 = (f32x4){__uint_as_float(w.x << 16), __uint_as_float(w.x & 0xffff0000u), __uint_as_float(w.y << 16), __uint_as_float(w.y & 0xffff0000u)};
;                         b1 = (f32x4){__uint_as_float(w.z << 16), __uint_as_float(w.z & 0xffff0000u), __uint_as_float(w.w << 16), __uint_as_float(w.w & 0xffff0000u)}; }
;                     const f32x4 o0 = b0 + g[bj][0] * acc[ai][bj][m][0], o1 = b1 + g[bj][1] * acc[ai][bj][m][1];
;                     if (of) { *(f32x4*)(opf + off + bj * 128) = o0; *(f32x4*)(opf + off + bj * 128 + 4) = o1; }
;                     else { u32x4 w; w.x = pkbf(o0[0], o0[1]); w.y = pkbf(o0[2], o0[3]); w.z = pkbf(o1[0], o1[1]); w.w = pkbf(o1[2], o1[3]); *(u32x4*)(oph + off + bj * 128) = w; } } }
.LBB0_918:
	s_andn2_b64 vcc, exec, s[10:11]
	s_cbranch_vccnz .LBB0_1047
	s_and_b64 vcc, exec, s[0:1]
	s_cbranch_vccnz .Lepi_dn_orig
	v_readlane_b32 s26, v240, 19
	s_nop 0
	s_cmp_eq_u32 s26, 0
	s_cbranch_scc1 .Lepi_dn_bf
	v_lshl_add_u32 v144, v176, 10, v174
	v_lshlrev_b32_e32 v145, 2, v144
	v_lshlrev_b32_e32 v144, 1, v144
	s_mov_b32 s8, s70
	s_mov_b32 s9, s71
	v_readfirstlane_b32 s10, v158
	v_readfirstlane_b32 s11, v159
	s_nop 4
	global_load_dwordx4 v[198:201], v144, s[8:9]
	global_load_dwordx4 v[202:205], v144, s[8:9] offset:256
	s_add_u32 s8, s8, 0x8000
	s_addc_u32 s9, s9, 0
	global_load_dwordx4 v[206:209], v144, s[8:9]
	global_load_dwordx4 v[210:213], v144, s[8:9] offset:256
	s_add_u32 s8, s8, 0x8000
	s_addc_u32 s9, s9, 0
	global_load_dwordx4 v[214:217], v144, s[8:9]
	global_load_dwordx4 v[218:221], v144, s[8:9] offset:256
	s_add_u32 s8, s8, 0x8000
	s_addc_u32 s9, s9, 0
	global_load_dwordx4 v[222:225], v144, s[8:9]
	global_load_dwordx4 v[226:229], v144, s[8:9] offset:256
	s_waitcnt vmcnt(7)
	v_lshlrev_b32_e32 v178, 16, v198
	v_and_b32_e32 v179, 0xffff0000, v198
	v_lshlrev_b32_e32 v180, 16, v199
	v_and_b32_e32 v181, 0xffff0000, v199
	v_lshlrev_b32_e32 v182, 16, v200
	v_and_b32_e32 v183, 0xffff0000, v200
	v_lshlrev_b32_e32 v184, 16, v201
	v_and_b32_e32 v185, 0xffff0000, v201
	v_pk_fma_f32 v[140:141], v[140:141], v[100:101], v[178:179]
	v_pk_fma_f32 v[142:143], v[142:143], v[102:103], v[180:181]
	v_pk_fma_f32 v[136:137], v[136:137], v[96:97], v[182:183]
	v_pk_fma_f32 v[138:139], v[138:139], v[98:99], v[184:185]
	s_add_u32 s8, s8, 0x28000
	s_addc_u32 s9, s9, 0
	global_load_dwordx4 v[198:201], v144, s[8:9]
	global_store_dwordx4 v145, v[140:143], s[10:11]
	global_store_dwordx4 v145, v[136:139], s[10:11] offset:16
	s_waitcnt vmcnt(9)
	v_lshlrev_b32_e32 v178, 16, v202
	v_and_b32_e32 v179, 0xffff0000, v202
	v_lshlrev_b32_e32 v180, 16, v203
	v_and_b32_e32 v181, 0xffff0000, v203
	v_lshlrev_b32_e32 v182, 16, v204
	v_and_b32_e32 v183, 0xffff0000, v204
	v_lshlrev_b32_e32 v184, 16, v205
	v_and_b32_e32 v185, 0xffff0000, v205
	v_pk_fma_f32 v[132:133], v[132:133], v[88:89], v[178:179]
	v_pk_fma_f32 v[134:135], v[134:135], v[90:91], v[180:181]
	v_pk_fma_f32 v[128:129], v[128:129], v[80:81], v[182:183]
	v_pk_fma_f32 v[130:131], v[130:131], v[82:83], v[184:185]
	global_load_dwordx4 v[202:205], v144, s[8:9] offset:256
	global_store_dwordx4 v145, v[132:135], s[10:11] offset:512
	global_store_dwordx4 v145, v[128:131], s[10:11] offset:528
	s_waitcnt vmcnt(11)
	v_lshlrev_b32_e32 v178, 16, v206
	v_and_b32_e32 v179, 0xffff0000, v206
	v_lshlrev_b32_e32 v180, 16, v207
	v_and_b32_e32 v181, 0xffff0000, v207
	v_lshlrev_b32_e32 v182, 16, v208
	v_and_b32_e32 v183, 0xffff0000, v208
	v_lshlrev_b32_e32 v184, 16, v209
	v_and_b32_e32 v185, 0xffff0000, v209
	v_pk_fma_f32 v[124:125], v[124:125], v[100:101], v[178:179]
	v_pk_fma_f32 v[126:127], v[126:127], v[102:103], v[180:181]
	v_pk_fma_f32 v[120:121], v[120:121], v[96:97], v[182:183]
	v_pk_fma_f32 v[122:123], v[122:123], v[98:99], v[184:185]
	s_add_u32 s8, s8, 0x8000
	s_addc_u32 s9, s9, 0
	global_load_dwordx4 v[206:209], v144, s[8:9]
	s_add_u32 s10, s10, 0x10000
	s_addc_u32 s11, s11, 0
	global_store_dwordx4 v145, v[124:127], s[10:11]
	global_store_dwordx4 v145, v[120:123], s[10:11] offset:16
	s_waitcnt vmcnt(13)
	v_lshlrev_b32_e32 v178, 16, v210
	v_and_b32_e32 v179, 0xffff0000, v210
	v_lshlrev_b32_e32 v180, 16, v211
	v_and_b32_e32 v181, 0xffff0000, v211
	v_lshlrev_b32_e32 v182, 16, v212
	v_and_b32_e32 v183, 0xffff0000, v212
	v_lshlrev_b32_e32 v184, 16, v213
	v_and_b32_e32 v185, 0xffff0000, v213
	v_pk_fma_f32 v[116:117], v[116:117], v[88:89], v[178:179]
	v_pk_fma_f32 v[118:119], v[118:119], v[90:91], v[180:181]
	v_pk_fma_f32 v[112:113], v[112:113], v[80:81], v[182:183]
	v_pk_fma_f32 v[114:115], v[114:115], v[82:83], v[184:185]
	global_load_dwordx4 v[210:213], v144, s[8:9] offset:256
	global_store_dwordx4 v145, v[116:119], s[10:11] offset:512
	global_store_dwordx4 v145, v[112:115], s[10:11] offset:528
	s_waitcnt vmcnt(15)
	v_lshlrev_b32_e32 v178, 16, v214
	v_and_b32_e32 v179, 0xffff0000, v214
	v_lshlrev_b32_e32 v180, 16, v215
	v_and_b32_e32 v181, 0xffff0000, v215
	v_lshlrev_b32_e32 v182, 16, v216
	v_and_b32_e32 v183, 0xffff0000, v216
	v_lshlrev_b32_e32 v184, 16, v217
	v_and_b32_e32 v185, 0xffff0000, v217
	v_pk_fma_f32 v[108:109], v[108:109], v[100:101], v[178:179]
	v_pk_fma_f32 v[110:111], v[110:111], v[102:103], v[180:181]
	v_pk_fma_f32 v[104:105], v[104:105], v[96:97], v[182:183]
	v_pk_fma_f32 v[106:107], v[106:107], v[98:99], v[184:185]
	s_add_u32 s8, s8, 0x8000
	s_addc_u32 s9, s9, 0
	global_load_dwordx4 v[214:217], v144, s[8:9]
	s_add_u32 s10, s10, 0x10000
	s_addc_u32 s11, s11, 0
	global_store_dwordx4 v145, v[108:111], s[10:11]
	global_store_dwordx4 v145, v[104:107], s[10:11] offset:16
	s_waitcnt vmcnt(17)
	v_lshlrev_b32_e32 v178, 16, v218
	v_and_b32_e32 v179, 0xffff0000, v218
	v_lshlrev_b32_e32 v180, 16, v219
	v_and_b32_e32 v181, 0xffff0000, v219
	v_lshlrev_b32_e32 v182, 16, v220
	v_and_b32_e32 v183, 0xffff0000, v220
	v_lshlrev_b32_e32 v184, 16, v221
	v_and_b32_e32 v185, 0xffff0000, v221
	v_pk_fma_f32 v[92:93], v[92:93], v[88:89], v[178:179]
	v_pk_fma_f32 v[94:95], v[94:95], v[90:91], v[180:181]
	v_pk_fma_f32 v[84:85], v[84:85], v[80:81], v[182:183]
	v_pk_fma_f32 v[86:87], v[86:87], v[82:83], v[184:185]
	global_load_dwordx4 v[218:221], v144, s[8:9] offset:256
	global_store_dwordx4 v145, v[92:95], s[10:11] offset:512
	global_store_dwordx4 v145, v[84:87], s[10:11] offset:528
	s_waitcnt vmcnt(19)
; __device__ __forceinline__ unsigned pkbf(float lo, float hi) { f32x2_t v = {lo, hi}; bf16x2_t b = __builtin_convertvector(v, bf16x2_t); return __builtin_bit_cast(unsigned, b); }
;     __device__ __forceinline__ void operator()(const f32x4 (&acc)[2][2][4][2], const pg8::Unit& u, int wr, int wc, int fr, int fq) const {
;     ...
;         for (int ai = 0; ai < 2; ++ai)
; #pragma unroll
;             for (int m = 0; m < 4; ++m) { const size_t off = (size_t)(row0 + ai * 128 + m * 16) * DM + col0;
; #pragma unroll
;                 for (int bj = 0; bj < 2; ++bj) {
;                     f32x4 b0, b1;
;                     if (bf) { b0 = *(const f32x4*)(bpf + off + bj * 128); b1 = *(const f32x4*)(bpf + off + bj * 128 + 4); }
;                     else { const u32x4 w = *(const u32x4*)(bph + off + bj * 128);
;                         b0 = (f32x4){__uint_as_float(w.x << 16), __uint_as_float(w.x & 0xffff0000u), __uint_as_float(w.y << 16), __uint_as_float(w.y & 0xffff0000u)};
;                         b1 = (f32x4){__uint_as_float(w.z << 16), __uint_as_float(w.z & 0xffff0000u), __uint_as_float(w.w << 16), __uint_as_float(w.w & 0xffff0000u)}; }
;                     const f32x4 o0 = b0 + g[bj][0] * acc[ai][bj][m][0], o1 = b1 + g[bj][1] * acc[ai][bj][m][1];
;                     if (of) { *(f32x4*)(opf + off + bj * 128) = o0; *(f32x4*)(opf + off + bj * 128 + 4) = o1; }
;                     else { u32x4 w; w.x = pkbf(o0[0], o0[1]); w.y = pkbf(o0[2], o0[3]); w.z = pkbf(o1[0], o1[1]); w.w = pkbf(o1[2], o1[3]); *(u32x4*)(oph + off + bj * 128) = w; } } }
	v_lshlrev_b32_e32 v178, 16, v222
	v_and_b32_e32 v179, 0xffff0000, v222
	v_lshlrev_b32_e32 v180, 16, v223
	v_and_b32_e32 v181, 0xffff0000, v223
	v_lshlrev_b32_e32 v182, 16, v224
	v_and_b32_e32 v183, 0xffff0000, v224
	v_lshlrev_b32_e32 v184, 16, v225
	v_and_b32_e32 v185, 0xffff0000, v225
	v_pk_fma_f32 v[76:77], v[76:77], v[100:101], v[178:179]
	v_pk_fma_f32 v[78:79], v[78:79], v[102:103], v[180:181]
	v_pk_fma_f32 v[72:73], v[72:73], v[96:97], v[182:183]
	v_pk_fma_f32 v[74:75], v[74:75], v[98:99], v[184:185]
	s_add_u32 s8, s8, 0x8000
	s_addc_u32 s9, s9, 0
	global_load_dwordx4 v[222:225], v144, s[8:9]
	s_add_u32 s10, s10, 0x10000
	s_addc_u32 s11, s11, 0
	global_store_dwordx4 v145, v[76:79], s[10:11]
	global_store_dwordx4 v145, v[72:75], s[10:11] offset:16
	s_waitcnt vmcnt(21)
	v_lshlrev_b32_e32 v178, 16, v226
	v_and_b32_e32 v179, 0xffff0000, v226
	v_lshlrev_b32_e32 v180, 16, v227
	v_and_b32_e32 v181, 0xffff0000, v227
	v_lshlrev_b32_e32 v182, 16, v228
	v_and_b32_e32 v183, 0xffff0000, v228
	v_lshlrev_b32_e32 v184, 16, v229
	v_and_b32_e32 v185, 0xffff0000, v229
	v_pk_fma_f32 v[68:69], v[68:69], v[88:89], v[178:179]
	v_pk_fma_f32 v[70:71], v[70:71], v[90:91], v[180:181]
	v_pk_fma_f32 v[64:65], v[64:65], v[80:81], v[182:183]
	v_pk_fma_f32 v[66:67], v[66:67], v[82:83], v[184:185]
	global_load_dwordx4 v[226:229], v144, s[8:9] offset:256
	global_store_dwordx4 v145, v[68:71], s[10:11] offset:512
	global_store_dwordx4 v145, v[64:67], s[10:11] offset:528
	s_waitcnt vmcnt(23)
	v_lshlrev_b32_e32 v178, 16, v198
	v_and_b32_e32 v179, 0xffff0000, v198
	v_lshlrev_b32_e32 v180, 16, v199
	v_and_b32_e32 v181, 0xffff0000, v199
	v_lshlrev_b32_e32 v182, 16, v200
	v_and_b32_e32 v183, 0xffff0000, v200
	v_lshlrev_b32_e32 v184, 16, v201
	v_and_b32_e32 v185, 0xffff0000, v201
	v_pk_fma_f32 v[60:61], v[60:61], v[100:101], v[178:179]
	v_pk_fma_f32 v[62:63], v[62:63], v[102:103], v[180:181]
	v_pk_fma_f32 v[56:57], v[56:57], v[96:97], v[182:183]
	v_pk_fma_f32 v[58:59], v[58:59], v[98:99], v[184:185]
	s_add_u32 s10, s10, 0x50000
	s_addc_u32 s11, s11, 0
	global_store_dwordx4 v145, v[60:63], s[10:11]
	global_store_dwordx4 v145, v[56:59], s[10:11] offset:16
	s_waitcnt vmcnt(22)
	v_lshlrev_b32_e32 v178, 16, v202
	v_and_b32_e32 v179, 0xffff0000, v202
	v_lshlrev_b32_e32 v180, 16, v203
	v_and_b32_e32 v181, 0xffff0000, v203
	v_lshlrev_b32_e32 v182, 16, v204
	v_and_b32_e32 v183, 0xffff0000, v204
	v_lshlrev_b32_e32 v184, 16, v205
	v_and_b32_e32 v185, 0xffff0000, v205
	v_pk_fma_f32 v[52:53], v[52:53], v[88:89], v[178:179]
	v_pk_fma_f32 v[54:55], v[54:55], v[90:91], v[180:181]
	v_pk_fma_f32 v[48:49], v[48:49], v[80:81], v[182:183]
	v_pk_fma_f32 v[50:51], v[50:51], v[82:83], v[184:185]
	global_store_dwordx4 v145, v[52:55], s[10:11] offset:512
	global_store_dwordx4 v145, v[48:51], s[10:11] offset:528
	s_waitcnt vmcnt(21)
	v_lshlrev_b32_e32 v178, 16, v206
	v_and_b32_e32 v179, 0xffff0000, v206
	v_lshlrev_b32_e32 v180, 16, v207
	v_and_b32_e32 v181, 0xffff0000, v207
	v_lshlrev_b32_e32 v182, 16, v208
	v_and_b32_e32 v183, 0xffff0000, v208
	v_lshlrev_b32_e32 v184, 16, v209
	v_and_b32_e32 v185, 0xffff0000, v209
	v_pk_fma_f32 v[44:45], v[44:45], v[100:101], v[178:179]
	v_pk_fma_f32 v[46:47], v[46:47], v[102:103], v[180:181]
	v_pk_fma_f32 v[40:41], v[40:41], v[96:97], v[182:183]
	v_pk_fma_f32 v[42:43], v[42:43], v[98:99], v[184:185]
	s_add_u32 s10, s10, 0x10000
	s_addc_u32 s11, s11, 0
	global_store_dwordx4 v145, v[44:47], s[10:11]
	global_store_dwordx4 v145, v[40:43], s[10:11] offset:16
	s_waitcnt vmcnt(20)
	v_lshlrev_b32_e32 v178, 16, v210
	v_and_b32_e32 v179, 0xffff0000, v210
	v_lshlrev_b32_e32 v180, 16, v211
	v_and_b32_e32 v181, 0xffff0000, v211
	v_lshlrev_b32_e32 v182, 16, v212
	v_and_b32_e32 v183, 0xffff0000, v212
	v_lshlrev_b32_e32 v184, 16, v213
	v_and_b32_e32 v185, 0xffff0000, v213
	v_pk_fma_f32 v[36:37], v[36:37], v[88:89], v[178:179]
	v_pk_fma_f32 v[38:39], v[38:39], v[90:91], v[180:181]
	v_pk_fma_f32 v[32:33], v[32:33], v[80:81], v[182:183]
	v_pk_fma_f32 v[34:35], v[34:35], v[82:83], v[184:185]
	global_store_dwordx4 v145, v[36:39], s[10:11] offset:512
	global_store_dwordx4 v145, v[32:35], s[10:11] offset:528
	s_waitcnt vmcnt(19)
	v_lshlrev_b32_e32 v178, 16, v214
	v_and_b32_e32 v179, 0xffff0000, v214
	v_lshlrev_b32_e32 v180, 16, v215
	v_and_b32_e32 v181, 0xffff0000, v215
	v_lshlrev_b32_e32 v182, 16, v216
	v_and_b32_e32 v183, 0xffff0000, v216
	v_lshlrev_b32_e32 v184, 16, v217
	v_and_b32_e32 v185, 0xffff0000, v217
	v_pk_fma_f32 v[28:29], v[28:29], v[100:101], v[178:179]
	v_pk_fma_f32 v[30:31], v[30:31], v[102:103], v[180:181]
	v_pk_fma_f32 v[24:25], v[24:25], v[96:97], v[182:183]
	v_pk_fma_f32 v[26:27], v[26:27], v[98:99], v[184:185]
	s_add_u32 s10, s10, 0x10000
	s_addc_u32 s11, s11, 0
	global_store_dwordx4 v145, v[28:31], s[10:11]
	global_store_dwordx4 v145, v[24:27], s[10:11] offset:16
	s_waitcnt vmcnt(18)
	v_lshlrev_b32_e32 v178, 16, v218
	v_and_b32_e32 v179, 0xffff0000, v218
	v_lshlrev_b32_e32 v180, 16, v219
	v_and_b32_e32 v181, 0xffff0000, v219
	v_lshlrev_b32_e32 v182, 16, v220
	v_and_b32_e32 v183, 0xffff0000, v220
	v_lshlrev_b32_e32 v184, 16, v221
	v_and_b32_e32 v185, 0xffff0000, v221
	v_pk_fma_f32 v[20:21], v[20:21], v[88:89], v[178:179]
	v_pk_fma_f32 v[22:23], v[22:23], v[90:91], v[180:181]
	v_pk_fma_f32 v[16:17], v[16:17], v[80:81], v[182:183]
	v_pk_fma_f32 v[18:19], v[18:19], v[82:83], v[184:185]
	global_store_dwordx4 v145, v[20:23], s[10:11] offset:512
	global_store_dwordx4 v145, v[16:19], s[10:11] offset:528
	s_waitcnt vmcnt(17)
	v_lshlrev_b32_e32 v178, 16, v222
	v_and_b32_e32 v179, 0xffff0000, v222
	v_lshlrev_b32_e32 v180, 16, v223
	v_and_b32_e32 v181, 0xffff0000, v223
	v_lshlrev_b32_e32 v182, 16, v224
	v_and_b32_e32 v183, 0xffff0000, v224
	v_lshlrev_b32_e32 v184, 16, v225
	v_and_b32_e32 v185, 0xffff0000, v225
	v_pk_fma_f32 v[12:13], v[12:13], v[100:101], v[178:179]
	v_pk_fma_f32 v[14:15], v[14:15], v[102:103], v[180:181]
	v_pk_fma_f32 v[8:9], v[8:9], v[96:97], v[182:183]
	v_pk_fma_f32 v[10:11], v[10:11], v[98:99], v[184:185]
	s_add_u32 s10, s10, 0x10000
	s_addc_u32 s11, s11, 0
	global_store_dwordx4 v145, v[12:15], s[10:11]
	global_store_dwordx4 v145, v[8:11], s[10:11] offset:16
	s_waitcnt vmcnt(16)
	v_lshlrev_b32_e32 v178, 16, v226
	v_and_b32_e32 v179, 0xffff0000, v226
	v_lshlrev_b32_e32 v180, 16, v227
	v_and_b32_e32 v181, 0xffff0000, v227
	v_lshlrev_b32_e32 v182, 16, v228
	v_and_b32_e32 v183, 0xffff0000, v228
	v_lshlrev_b32_e32 v184, 16, v229
	v_and_b32_e32 v185, 0xffff0000, v229
	v_pk_fma_f32 v[4:5], v[4:5], v[88:89], v[178:179]
	v_pk_fma_f32 v[6:7], v[6:7], v[90:91], v[180:181]
	v_pk_fma_f32 v[0:1], v[0:1], v[80:81], v[182:183]
	v_pk_fma_f32 v[2:3], v[2:3], v[82:83], v[184:185]
	global_store_dwordx4 v145, v[4:7], s[10:11] offset:512
	global_store_dwordx4 v145, v[0:3], s[10:11] offset:528
	s_branch .LBB0_1047
; __device__ __forceinline__ unsigned pkbf(float lo, float hi) { f32x2_t v = {lo, hi}; bf16x2_t b = __builtin_convertvector(v, bf16x2_t); return __builtin_bit_cast(unsigned, b); }
;     __device__ __forceinline__ void operator()(const f32x4 (&acc)[2][2][4][2], const pg8::Unit& u, int wr, int wc, int fr, int fq) const {
;     ...
;         for (int ai = 0; ai < 2; ++ai)
; #pragma unroll
;             for (int m = 0; m < 4; ++m) { const size_t off = (size_t)(row0 + ai * 128 + m * 16) * DM + col0;
; #pragma unroll
;                 for (int bj = 0; bj < 2; ++bj) {
;                     f32x4 b0, b1;
;                     if (bf) { b0 = *(const f32x4*)(bpf + off + bj * 128); b1 = *(const f32x4*)(bpf + off + bj * 128 + 4); }
;                     else { const u32x4 w = *(const u32x4*)(bph + off + bj * 128);
;                         b0 = (f32x4){__uint_as_float(w.x << 16), __uint_as_float(w.x & 0xffff0000u), __uint_as_float(w.y << 16), __uint_as_float(w.y & 0xffff0000u)};
;                         b1 = (f32x4){__uint_as_float(w.z << 16), __uint_as_float(w.z & 0xffff0000u), __uint_as_float(w.w << 16), __uint_as_float(w.w & 0xffff0000u)}; }
;                     const f32x4 o0 = b0 + g[bj][0] * acc[ai][bj][m][0], o1 = b1 + g[bj][1] * acc[ai][bj][m][1];
;                     if (of) { *(f32x4*)(opf + off + bj * 128) = o0; *(f32x4*)(opf + off + bj * 128 + 4) = o1; }
;                     else { u32x4 w; w.x = pkbf(o0[0], o0[1]); w.y = pkbf(o0[2], o0[3]); w.z = pkbf(o1[0], o1[1]); w.w = pkbf(o1[2], o1[3]); *(u32x4*)(oph + off + bj * 128) = w; } } }
.Lepi_dn_bf:
	v_lshl_add_u32 v144, v176, 10, v174
	v_lshlrev_b32_e32 v145, 2, v144
	v_lshlrev_b32_e32 v144, 1, v144
	s_mov_b32 s8, s70
	s_mov_b32 s9, s71
	v_readfirstlane_b32 s10, v158
	v_readfirstlane_b32 s11, v159
	s_nop 4
	global_load_dwordx4 v[198:201], v144, s[8:9]
	global_load_dwordx4 v[202:205], v144, s[8:9] offset:256
	s_add_u32 s8, s8, 0x8000
	s_addc_u32 s9, s9, 0
	global_load_dwordx4 v[206:209], v144, s[8:9]
	global_load_dwordx4 v[210:213], v144, s[8:9] offset:256
	s_add_u32 s8, s8, 0x8000
	s_addc_u32 s9, s9, 0
	global_load_dwordx4 v[214:217], v144, s[8:9]
	global_load_dwordx4 v[218:221], v144, s[8:9] offset:256
	s_add_u32 s8, s8, 0x8000
	s_addc_u32 s9, s9, 0
	global_load_dwordx4 v[222:225], v144, s[8:9]
	global_load_dwordx4 v[226:229], v144, s[8:9] offset:256
	s_waitcnt vmcnt(7)
	v_lshlrev_b32_e32 v178, 16, v198
	v_and_b32_e32 v179, 0xffff0000, v198
	v_lshlrev_b32_e32 v180, 16, v199
	v_and_b32_e32 v181, 0xffff0000, v199
	v_lshlrev_b32_e32 v182, 16, v200
	v_and_b32_e32 v183, 0xffff0000, v200
	v_lshlrev_b32_e32 v184, 16, v201
	v_and_b32_e32 v185, 0xffff0000, v201
	v_pk_fma_f32 v[140:141], v[140:141], v[100:101], v[178:179]
	v_pk_fma_f32 v[142:143], v[142:143], v[102:103], v[180:181]
	v_pk_fma_f32 v[136:137], v[136:137], v[96:97], v[182:183]
	v_pk_fma_f32 v[138:139], v[138:139], v[98:99], v[184:185]
	s_add_u32 s8, s8, 0x28000
	s_addc_u32 s9, s9, 0
	global_load_dwordx4 v[198:201], v144, s[8:9]
	v_cvt_pk_bf16_f32 v140, v140, v141
	v_cvt_pk_bf16_f32 v141, v142, v143
	v_cvt_pk_bf16_f32 v142, v136, v137
	v_cvt_pk_bf16_f32 v143, v138, v139
	global_store_dwordx4 v144, v[140:143], s[10:11]
	s_waitcnt vmcnt(8)
	v_lshlrev_b32_e32 v178, 16, v202
	v_and_b32_e32 v179, 0xffff0000, v202
	v_lshlrev_b32_e32 v180, 16, v203
	v_and_b32_e32 v181, 0xffff0000, v203
	v_lshlrev_b32_e32 v182, 16, v204
	v_and_b32_e32 v183, 0xffff0000, v204
	v_lshlrev_b32_e32 v184, 16, v205
	v_and_b32_e32 v185, 0xffff0000, v205
	v_pk_fma_f32 v[132:133], v[132:133], v[88:89], v[178:179]
	v_pk_fma_f32 v[134:135], v[134:135], v[90:91], v[180:181]
	v_pk_fma_f32 v[128:129], v[128:129], v[80:81], v[182:183]
	v_pk_fma_f32 v[130:131], v[130:131], v[82:83], v[184:185]
	global_load_dwordx4 v[202:205], v144, s[8:9] offset:256
	v_cvt_pk_bf16_f32 v132, v132, v133
	v_cvt_pk_bf16_f32 v133, v134, v135
	v_cvt_pk_bf16_f32 v134, v128, v129
	v_cvt_pk_bf16_f32 v135, v130, v131
	global_store_dwordx4 v144, v[132:135], s[10:11] offset:256
	s_waitcnt vmcnt(9)
	v_lshlrev_b32_e32 v178, 16, v206
	v_and_b32_e32 v179, 0xffff0000, v206
	v_lshlrev_b32_e32 v180, 16, v207
	v_and_b32_e32 v181, 0xffff0000, v207
	v_lshlrev_b32_e32 v182, 16, v208
	v_and_b32_e32 v183, 0xffff0000, v208
	v_lshlrev_b32_e32 v184, 16, v209
	v_and_b32_e32 v185, 0xffff0000, v209
	v_pk_fma_f32 v[124:125], v[124:125], v[100:101], v[178:179]
	v_pk_fma_f32 v[126:127], v[126:127], v[102:103], v[180:181]
	v_pk_fma_f32 v[120:121], v[120:121], v[96:97], v[182:183]
	v_pk_fma_f32 v[122:123], v[122:123], v[98:99], v[184:185]
	s_add_u32 s8, s8, 0x8000
	s_addc_u32 s9, s9, 0
	global_load_dwordx4 v[206:209], v144, s[8:9]
	s_add_u32 s10, s10, 0x8000
	s_addc_u32 s11, s11, 0
	v_cvt_pk_bf16_f32 v124, v124, v125
	v_cvt_pk_bf16_f32 v125, v126, v127
	v_cvt_pk_bf16_f32 v126, v120, v121
	v_cvt_pk_bf16_f32 v127, v122, v123
	global_store_dwordx4 v144, v[124:127], s[10:11]
	s_waitcnt vmcnt(10)
	v_lshlrev_b32_e32 v178, 16, v210
	v_and_b32_e32 v179, 0xffff0000, v210
	v_lshlrev_b32_e32 v180, 16, v211
	v_and_b32_e32 v181, 0xffff0000, v211
	v_lshlrev_b32_e32 v182, 16, v212
	v_and_b32_e32 v183, 0xffff0000, v212
	v_lshlrev_b32_e32 v184, 16, v213
	v_and_b32_e32 v185, 0xffff0000, v213
	v_pk_fma_f32 v[116:117], v[116:117], v[88:89], v[178:179]
	v_pk_fma_f32 v[118:119], v[118:119], v[90:91], v[180:181]
	v_pk_fma_f32 v[112:113], v[112:113], v[80:81], v[182:183]
	v_pk_fma_f32 v[114:115], v[114:115], v[82:83], v[184:185]
	global_load_dwordx4 v[210:213], v144, s[8:9] offset:256
	v_cvt_pk_bf16_f32 v116, v116, v117
	v_cvt_pk_bf16_f32 v117, v118, v119
	v_cvt_pk_bf16_f32 v118, v112, v113
	v_cvt_pk_bf16_f32 v119, v114, v115
	global_store_dwordx4 v144, v[116:119], s[10:11] offset:256
	s_waitcnt vmcnt(11)
	v_lshlrev_b32_e32 v178, 16, v214
	v_and_b32_e32 v179, 0xffff0000, v214
	v_lshlrev_b32_e32 v180, 16, v215
	v_and_b32_e32 v181, 0xffff0000, v215
	v_lshlrev_b32_e32 v182, 16, v216
	v_and_b32_e32 v183, 0xffff0000, v216
	v_lshlrev_b32_e32 v184, 16, v217
	v_and_b32_e32 v185, 0xffff0000, v217
	v_pk_fma_f32 v[108:109], v[108:109], v[100:101], v[178:179]
	v_pk_fma_f32 v[110:111], v[110:111], v[102:103], v[180:181]
	v_pk_fma_f32 v[104:105], v[104:105], v[96:97], v[182:183]
	v_pk_fma_f32 v[106:107], v[106:107], v[98:99], v[184:185]
	s_add_u32 s8, s8, 0x8000
	s_addc_u32 s9, s9, 0
	global_load_dwordx4 v[214:217], v144, s[8:9]
	s_add_u32 s10, s10, 0x8000
	s_addc_u32 s11, s11, 0
	v_cvt_pk_bf16_f32 v108, v108, v109
	v_cvt_pk_bf16_f32 v109, v110, v111
	v_cvt_pk_bf16_f32 v110, v104, v105
	v_cvt_pk_bf16_f32 v111, v106, v107
	global_store_dwordx4 v144, v[108:111], s[10:11]
	s_waitcnt vmcnt(12)
	v_lshlrev_b32_e32 v178, 16, v218
	v_and_b32_e32 v179, 0xffff0000, v218
	v_lshlrev_b32_e32 v180, 16, v219
	v_and_b32_e32 v181, 0xffff0000, v219
	v_lshlrev_b32_e32 v182, 16, v220
	v_and_b32_e32 v183, 0xffff0000, v220
	v_lshlrev_b32_e32 v184, 16, v221
	v_and_b32_e32 v185, 0xffff0000, v221
	v_pk_fma_f32 v[92:93], v[92:93], v[88:89], v[178:179]
	v_pk_fma_f32 v[94:95], v[94:95], v[90:91], v[180:181]
	v_pk_fma_f32 v[84:85], v[84:85], v[80:81], v[182:183]
	v_pk_fma_f32 v[86:87], v[86:87], v[82:83], v[184:185]
	global_load_dwordx4 v[218:221], v144, s[8:9] offset:256
	v_cvt_pk_bf16_f32 v92, v92, v93
	v_cvt_pk_bf16_f32 v93, v94, v95
	v_cvt_pk_bf16_f32 v94, v84, v85
	v_cvt_pk_bf16_f32 v95, v86, v87
	global_store_dwordx4 v144, v[92:95], s[10:11] offset:256
	s_waitcnt vmcnt(13)
; __device__ __forceinline__ unsigned pkbf(float lo, float hi) { f32x2_t v = {lo, hi}; bf16x2_t b = __builtin_convertvector(v, bf16x2_t); return __builtin_bit_cast(unsigned, b); }
;     __device__ __forceinline__ void operator()(const f32x4 (&acc)[2][2][4][2], const pg8::Unit& u, int wr, int wc, int fr, int fq) const {
;     ...
; #pragma unroll
;         for (int ai = 0; ai < 2; ++ai)
; #pragma unroll
;             for (int m = 0; m < 4; ++m) { const size_t off = (size_t)(row0 + ai * 128 + m * 16) * DM + col0;
; #pragma unroll
;                 for (int bj = 0; bj < 2; ++bj) {
;                     f32x4 b0, b1;
;                     if (bf) { b0 = *(const f32x4*)(bpf + off + bj * 128); b1 = *(const f32x4*)(bpf + off + bj * 128 + 4); }
;                     else { const u32x4 w = *(const u32x4*)(bph + off + bj * 128);
;                         b0 = (f32x4){__uint_as_float(w.x << 16), __uint_as_float(w.x & 0xffff0000u), __uint_as_float(w.y << 16), __uint_as_float(w.y & 0xffff0000u)};
;                         b1 = (f32x4){__uint_as_float(w.z << 16), __uint_as_float(w.z & 0xffff0000u), __uint_as_float(w.w << 16), __uint_as_float(w.w & 0xffff0000u)}; }
;                     const f32x4 o0 = b0 + g[bj][0] * acc[ai][bj][m][0], o1 = b1 + g[bj][1] * acc[ai][bj][m][1];
;                     if (of) { *(f32x4*)(opf + off + bj * 128) = o0; *(f32x4*)(opf + off + bj * 128 + 4) = o1; }
;                     else { u32x4 w; w.x = pkbf(o0[0], o0[1]); w.y = pkbf(o0[2], o0[3]); w.z = pkbf(o1[0], o1[1]); w.w = pkbf(o1[2], o1[3]); *(u32x4*)(oph + off + bj * 128) = w; } } }
	v_lshlrev_b32_e32 v178, 16, v222
	v_and_b32_e32 v179, 0xffff0000, v222
	v_lshlrev_b32_e32 v180, 16, v223
	v_and_b32_e32 v181, 0xffff0000, v223
	v_lshlrev_b32_e32 v182, 16, v224
	v_and_b32_e32 v183, 0xffff0000, v224
	v_lshlrev_b32_e32 v184, 16, v225
	v_and_b32_e32 v185, 0xffff0000, v225
	v_pk_fma_f32 v[76:77], v[76:77], v[100:101], v[178:179]
	v_pk_fma_f32 v[78:79], v[78:79], v[102:103], v[180:181]
	v_pk_fma_f32 v[72:73], v[72:73], v[96:97], v[182:183]
	v_pk_fma_f32 v[74:75], v[74:75], v[98:99], v[184:185]
	s_add_u32 s8, s8, 0x8000
	s_addc_u32 s9, s9, 0
	global_load_dwordx4 v[222:225], v144, s[8:9]
	s_add_u32 s10, s10, 0x8000
	s_addc_u32 s11, s11, 0
	v_cvt_pk_bf16_f32 v76, v76, v77
	v_cvt_pk_bf16_f32 v77, v78, v79
	v_cvt_pk_bf16_f32 v78, v72, v73
	v_cvt_pk_bf16_f32 v79, v74, v75
	global_store_dwordx4 v144, v[76:79], s[10:11]
	s_waitcnt vmcnt(14)
	v_lshlrev_b32_e32 v178, 16, v226
	v_and_b32_e32 v179, 0xffff0000, v226
	v_lshlrev_b32_e32 v180, 16, v227
	v_and_b32_e32 v181, 0xffff0000, v227
	v_lshlrev_b32_e32 v182, 16, v228
	v_and_b32_e32 v183, 0xffff0000, v228
	v_lshlrev_b32_e32 v184, 16, v229
	v_and_b32_e32 v185, 0xffff0000, v229
	v_pk_fma_f32 v[68:69], v[68:69], v[88:89], v[178:179]
	v_pk_fma_f32 v[70:71], v[70:71], v[90:91], v[180:181]
	v_pk_fma_f32 v[64:65], v[64:65], v[80:81], v[182:183]
	v_pk_fma_f32 v[66:67], v[66:67], v[82:83], v[184:185]
	global_load_dwordx4 v[226:229], v144, s[8:9] offset:256
	v_cvt_pk_bf16_f32 v68, v68, v69
	v_cvt_pk_bf16_f32 v69, v70, v71
	v_cvt_pk_bf16_f32 v70, v64, v65
	v_cvt_pk_bf16_f32 v71, v66, v67
	global_store_dwordx4 v144, v[68:71], s[10:11] offset:256
	s_waitcnt vmcnt(15)
	v_lshlrev_b32_e32 v178, 16, v198
	v_and_b32_e32 v179, 0xffff0000, v198
	v_lshlrev_b32_e32 v180, 16, v199
	v_and_b32_e32 v181, 0xffff0000, v199
	v_lshlrev_b32_e32 v182, 16, v200
	v_and_b32_e32 v183, 0xffff0000, v200
	v_lshlrev_b32_e32 v184, 16, v201
	v_and_b32_e32 v185, 0xffff0000, v201
	v_pk_fma_f32 v[60:61], v[60:61], v[100:101], v[178:179]
	v_pk_fma_f32 v[62:63], v[62:63], v[102:103], v[180:181]
	v_pk_fma_f32 v[56:57], v[56:57], v[96:97], v[182:183]
	v_pk_fma_f32 v[58:59], v[58:59], v[98:99], v[184:185]
	s_add_u32 s10, s10, 0x28000
	s_addc_u32 s11, s11, 0
	v_cvt_pk_bf16_f32 v60, v60, v61
	v_cvt_pk_bf16_f32 v61, v62, v63
	v_cvt_pk_bf16_f32 v62, v56, v57
	v_cvt_pk_bf16_f32 v63, v58, v59
	global_store_dwordx4 v144, v[60:63], s[10:11]
	s_waitcnt vmcnt(14)
	v_lshlrev_b32_e32 v178, 16, v202
	v_and_b32_e32 v179, 0xffff0000, v202
	v_lshlrev_b32_e32 v180, 16, v203
	v_and_b32_e32 v181, 0xffff0000, v203
	v_lshlrev_b32_e32 v182, 16, v204
	v_and_b32_e32 v183, 0xffff0000, v204
	v_lshlrev_b32_e32 v184, 16, v205
	v_and_b32_e32 v185, 0xffff0000, v205
	v_pk_fma_f32 v[52:53], v[52:53], v[88:89], v[178:179]
	v_pk_fma_f32 v[54:55], v[54:55], v[90:91], v[180:181]
	v_pk_fma_f32 v[48:49], v[48:49], v[80:81], v[182:183]
	v_pk_fma_f32 v[50:51], v[50:51], v[82:83], v[184:185]
	v_cvt_pk_bf16_f32 v52, v52, v53
	v_cvt_pk_bf16_f32 v53, v54, v55
	v_cvt_pk_bf16_f32 v54, v48, v49
	v_cvt_pk_bf16_f32 v55, v50, v51
	global_store_dwordx4 v144, v[52:55], s[10:11] offset:256
	s_waitcnt vmcnt(13)
	v_lshlrev_b32_e32 v178, 16, v206
	v_and_b32_e32 v179, 0xffff0000, v206
	v_lshlrev_b32_e32 v180, 16, v207
	v_and_b32_e32 v181, 0xffff0000, v207
	v_lshlrev_b32_e32 v182, 16, v208
	v_and_b32_e32 v183, 0xffff0000, v208
	v_lshlrev_b32_e32 v184, 16, v209
	v_and_b32_e32 v185, 0xffff0000, v209
	v_pk_fma_f32 v[44:45], v[44:45], v[100:101], v[178:179]
	v_pk_fma_f32 v[46:47], v[46:47], v[102:103], v[180:181]
	v_pk_fma_f32 v[40:41], v[40:41], v[96:97], v[182:183]
	v_pk_fma_f32 v[42:43], v[42:43], v[98:99], v[184:185]
	s_add_u32 s10, s10, 0x8000
	s_addc_u32 s11, s11, 0
	v_cvt_pk_bf16_f32 v44, v44, v45
	v_cvt_pk_bf16_f32 v45, v46, v47
	v_cvt_pk_bf16_f32 v46, v40, v41
	v_cvt_pk_bf16_f32 v47, v42, v43
	global_store_dwordx4 v144, v[44:47], s[10:11]
	s_waitcnt vmcnt(12)
; __device__ __forceinline__ unsigned pkbf(float lo, float hi) { f32x2_t v = {lo, hi}; bf16x2_t b = __builtin_convertvector(v, bf16x2_t); return __builtin_bit_cast(unsigned, b); }
;     __device__ __forceinline__ void operator()(const f32x4 (&acc)[2][2][4][2], const pg8::Unit& u, int wr, int wc, int fr, int fq) const {
;     ...
; #pragma unroll
;         for (int ai = 0; ai < 2; ++ai)
; #pragma unroll
;             for (int m = 0; m < 4; ++m) { const size_t off = (size_t)(row0 + ai * 128 + m * 16) * DM + col0;
; #pragma unroll
;                 for (int bj = 0; bj < 2; ++bj) {
;                     f32x4 b0, b1;
;                     if (bf) { b0 = *(const f32x4*)(bpf + off + bj * 128); b1 = *(const f32x4*)(bpf + off + bj * 128 + 4); }
;                     else { const u32x4 w = *(const u32x4*)(bph + off + bj * 128);
;                         b0 = (f32x4){__uint_as_float(w.x << 16), __uint_as_float(w.x & 0xffff0000u), __uint_as_float(w.y << 16), __uint_as_float(w.y & 0xffff0000u)};
;                         b1 = (f32x4){__uint_as_float(w.z << 16), __uint_as_float(w.z & 0xffff0000u), __uint_as_float(w.w << 16), __uint_as_float(w.w & 0xffff0000u)}; }
;                     const f32x4 o0 = b0 + g[bj][0] * acc[ai][bj][m][0], o1 = b1 + g[bj][1] * acc[ai][bj][m][1];
;                     if (of) { *(f32x4*)(opf + off + bj * 128) = o0; *(f32x4*)(opf + off + bj * 128 + 4) = o1; }
;                     else { u32x4 w; w.x = pkbf(o0[0], o0[1]); w.y = pkbf(o0[2], o0[3]); w.z = pkbf(o1[0], o1[1]); w.w = pkbf(o1[2], o1[3]); *(u32x4*)(oph + off + bj * 128) = w; } } }
	v_lshlrev_b32_e32 v178, 16, v210
	v_and_b32_e32 v179, 0xffff0000, v210
	v_lshlrev_b32_e32 v180, 16, v211
	v_and_b32_e32 v181, 0xffff0000, v211
	v_lshlrev_b32_e32 v182, 16, v212
	v_and_b32_e32 v183, 0xffff0000, v212
	v_lshlrev_b32_e32 v184, 16, v213
	v_and_b32_e32 v185, 0xffff0000, v213
	v_pk_fma_f32 v[36:37], v[36:37], v[88:89], v[178:179]
	v_pk_fma_f32 v[38:39], v[38:39], v[90:91], v[180:181]
	v_pk_fma_f32 v[32:33], v[32:33], v[80:81], v[182:183]
	v_pk_fma_f32 v[34:35], v[34:35], v[82:83], v[184:185]
	v_cvt_pk_bf16_f32 v36, v36, v37
	v_cvt_pk_bf16_f32 v37, v38, v39
	v_cvt_pk_bf16_f32 v38, v32, v33
	v_cvt_pk_bf16_f32 v39, v34, v35
	global_store_dwordx4 v144, v[36:39], s[10:11] offset:256
	s_waitcnt vmcnt(11)
	v_lshlrev_b32_e32 v178, 16, v214
	v_and_b32_e32 v179, 0xffff0000, v214
	v_lshlrev_b32_e32 v180, 16, v215
	v_and_b32_e32 v181, 0xffff0000, v215
	v_lshlrev_b32_e32 v182, 16, v216
	v_and_b32_e32 v183, 0xffff0000, v216
	v_lshlrev_b32_e32 v184, 16, v217
	v_and_b32_e32 v185, 0xffff0000, v217
	v_pk_fma_f32 v[28:29], v[28:29], v[100:101], v[178:179]
	v_pk_fma_f32 v[30:31], v[30:31], v[102:103], v[180:181]
	v_pk_fma_f32 v[24:25], v[24:25], v[96:97], v[182:183]
	v_pk_fma_f32 v[26:27], v[26:27], v[98:99], v[184:185]
	s_add_u32 s10, s10, 0x8000
	s_addc_u32 s11, s11, 0
	v_cvt_pk_bf16_f32 v28, v28, v29
	v_cvt_pk_bf16_f32 v29, v30, v31
	v_cvt_pk_bf16_f32 v30, v24, v25
	v_cvt_pk_bf16_f32 v31, v26, v27
	global_store_dwordx4 v144, v[28:31], s[10:11]
	s_waitcnt vmcnt(10)
	v_lshlrev_b32_e32 v178, 16, v218
	v_and_b32_e32 v179, 0xffff0000, v218
	v_lshlrev_b32_e32 v180, 16, v219
	v_and_b32_e32 v181, 0xffff0000, v219
	v_lshlrev_b32_e32 v182, 16, v220
	v_and_b32_e32 v183, 0xffff0000, v220
	v_lshlrev_b32_e32 v184, 16, v221
	v_and_b32_e32 v185, 0xffff0000, v221
	v_pk_fma_f32 v[20:21], v[20:21], v[88:89], v[178:179]
	v_pk_fma_f32 v[22:23], v[22:23], v[90:91], v[180:181]
	v_pk_fma_f32 v[16:17], v[16:17], v[80:81], v[182:183]
	v_pk_fma_f32 v[18:19], v[18:19], v[82:83], v[184:185]
	v_cvt_pk_bf16_f32 v20, v20, v21
	v_cvt_pk_bf16_f32 v21, v22, v23
	v_cvt_pk_bf16_f32 v22, v16, v17
	v_cvt_pk_bf16_f32 v23, v18, v19
	global_store_dwordx4 v144, v[20:23], s[10:11] offset:256
	s_waitcnt vmcnt(9)
	v_lshlrev_b32_e32 v178, 16, v222
	v_and_b32_e32 v179, 0xffff0000, v222
	v_lshlrev_b32_e32 v180, 16, v223
	v_and_b32_e32 v181, 0xffff0000, v223
	v_lshlrev_b32_e32 v182, 16, v224
	v_and_b32_e32 v183, 0xffff0000, v224
	v_lshlrev_b32_e32 v184, 16, v225
	v_and_b32_e32 v185, 0xffff0000, v225
	v_pk_fma_f32 v[12:13], v[12:13], v[100:101], v[178:179]
	v_pk_fma_f32 v[14:15], v[14:15], v[102:103], v[180:181]
	v_pk_fma_f32 v[8:9], v[8:9], v[96:97], v[182:183]
	v_pk_fma_f32 v[10:11], v[10:11], v[98:99], v[184:185]
	s_add_u32 s10, s10, 0x8000
	s_addc_u32 s11, s11, 0
	v_cvt_pk_bf16_f32 v12, v12, v13
	v_cvt_pk_bf16_f32 v13, v14, v15
	v_cvt_pk_bf16_f32 v14, v8, v9
	v_cvt_pk_bf16_f32 v15, v10, v11
	global_store_dwordx4 v144, v[12:15], s[10:11]
	s_waitcnt vmcnt(8)
	v_lshlrev_b32_e32 v178, 16, v226
	v_and_b32_e32 v179, 0xffff0000, v226
	v_lshlrev_b32_e32 v180, 16, v227
	v_and_b32_e32 v181, 0xffff0000, v227
	v_lshlrev_b32_e32 v182, 16, v228
	v_and_b32_e32 v183, 0xffff0000, v228
	v_lshlrev_b32_e32 v184, 16, v229
	v_and_b32_e32 v185, 0xffff0000, v229
	v_pk_fma_f32 v[4:5], v[4:5], v[88:89], v[178:179]
	v_pk_fma_f32 v[6:7], v[6:7], v[90:91], v[180:181]
	v_pk_fma_f32 v[0:1], v[0:1], v[80:81], v[182:183]
	v_pk_fma_f32 v[2:3], v[2:3], v[82:83], v[184:185]
	v_cvt_pk_bf16_f32 v4, v4, v5
	v_cvt_pk_bf16_f32 v5, v6, v7
	v_cvt_pk_bf16_f32 v6, v0, v1
	v_cvt_pk_bf16_f32 v7, v2, v3
	global_store_dwordx4 v144, v[4:7], s[10:11] offset:256
	s_branch .LBB0_1047
.Lepi_dn_orig:
	v_lshlrev_b64 v[144:145], 10, v[176:177]
	s_and_b64 s[8:9], s[0:1], exec
	v_lshl_add_u64 v[184:185], v[144:145], 0, v[174:175]
	s_cselect_b32 s23, s73, s71
	s_cselect_b32 s22, s72, s70
	v_lshl_add_u64 v[180:181], v[184:185], 1, s[70:71]
	s_mov_b64 s[8:9], -1
	s_and_b64 vcc, exec, s[24:25]
	s_cbranch_vccz .LBB0_921
	global_load_dwordx4 v[144:147], v[180:181], off
	s_mov_b64 s[8:9], 0
	s_waitcnt vmcnt(0)
	v_lshlrev_b32_e32 v148, 16, v144
	v_and_b32_e32 v149, 0xffff0000, v144
	v_lshlrev_b32_e32 v150, 16, v145
	v_and_b32_e32 v151, 0xffff0000, v145
	v_lshlrev_b32_e32 v144, 16, v146
	v_and_b32_e32 v145, 0xffff0000, v146
	v_lshlrev_b32_e32 v146, 16, v147
	v_and_b32_e32 v147, 0xffff0000, v147
